# nt also on phase E row reads (RAW, gates) and adaLN GEMV weight rows
# speedup vs baseline: 1.0222x; 1.0060x over previous
.LBB0_34:
	s_mov_b32 s46, 0xfffb8000
	v_add_co_u32_e64 v24, s[46:47], s46, v10
	v_add_co_u32_e32 v22, vcc, 0xfffac000, v10
	s_nop 0
	v_addc_co_u32_e64 v25, s[46:47], -1, v11, s[46:47]
	s_mov_b32 s46, 0xfffc4000
	s_nop 0
	v_add_co_u32_e64 v26, s[46:47], s46, v10
	v_addc_co_u32_e32 v23, vcc, -1, v11, vcc
	s_nop 0
	v_addc_co_u32_e64 v27, s[46:47], -1, v11, s[46:47]
	s_mov_b32 s46, 0xfffd0000
	s_nop 0
	v_add_co_u32_e64 v28, s[46:47], s46, v10
	s_nop 1
	v_addc_co_u32_e64 v29, s[46:47], -1, v11, s[46:47]
	s_mov_b32 s46, 0xfffdc000
	s_nop 0
	v_add_co_u32_e64 v30, s[46:47], s46, v10
	s_nop 1
	v_addc_co_u32_e64 v31, s[46:47], -1, v11, s[46:47]
	s_mov_b32 s46, 0xfffe8000
	s_nop 0
	v_add_co_u32_e64 v32, s[46:47], s46, v10
	s_nop 1
	v_addc_co_u32_e64 v33, s[46:47], -1, v11, s[46:47]
	s_mov_b32 s46, 0xffff4000
	s_nop 0
	v_add_co_u32_e64 v34, s[46:47], s46, v10
	s_nop 1
	v_addc_co_u32_e64 v35, s[46:47], -1, v11, s[46:47]
	global_load_dword v62, v[24:25], off nt
	global_load_dword v64, v[26:27], off nt
	global_load_dword v66, v[28:29], off nt
	global_load_dword v68, v[30:31], off nt
	global_load_dword v70, v[22:23], off nt
	global_load_dword v72, v[32:33], off nt
	global_load_dword v74, v[34:35], off nt
	global_load_dword v76, v[10:11], off nt
	s_add_i32 s46, s2, s0
	v_mov_b32_e32 v50, s46
	s_add_i32 s49, s46, 0x10800
	s_add_i32 s50, s46, 0x10810
	ds_read_b128 v[22:25], v50 offset:2048
	ds_read_b128 v[26:29], v50 offset:2064
	v_mov_b32_e32 v54, s49
	ds_read_b128 v[30:33], v50 offset:18432
	ds_read_b128 v[34:37], v50 offset:18448
	ds_read_b128 v[38:41], v50 offset:34816
	ds_read_b128 v[42:45], v50 offset:34832
	ds_read_b128 v[46:49], v50 offset:51200
	ds_read_b128 v[50:53], v50 offset:51216
	v_mov_b32_e32 v58, s50
	ds_read_b128 v[54:57], v54
	ds_read_b128 v[58:61], v58
	s_waitcnt lgkmcnt(9)
	v_mov_b32_e32 v78, v22
	s_waitcnt lgkmcnt(7)
	v_mov_b32_e32 v79, v30
	s_waitcnt lgkmcnt(5)
	v_mov_b32_e32 v80, v38
	s_waitcnt lgkmcnt(3)
	v_mov_b32_e32 v81, v46
	v_mov_b32_e32 v30, v23
	v_mov_b32_e32 v46, v39
	v_mov_b32_e32 v22, v24
	v_mov_b32_e32 v23, v32
	v_mov_b32_e32 v38, v40
	v_mov_b32_e32 v39, v48
	v_mov_b32_e32 v32, v25
	v_mov_b32_e32 v48, v41
	v_mov_b32_e32 v24, v26
	v_mov_b32_e32 v25, v34
	v_mov_b32_e32 v40, v42
	s_waitcnt lgkmcnt(2)
	v_mov_b32_e32 v41, v50
	v_mov_b32_e32 v34, v27
	v_mov_b32_e32 v50, v43
	v_mov_b32_e32 v26, v28
	v_mov_b32_e32 v27, v36
	v_mov_b32_e32 v42, v44
	v_mov_b32_e32 v43, v52
	s_add_i32 s0, s0, 32
	s_mov_b64 s[46:47], 0x60000
	v_mov_b32_e32 v36, v29
	v_mov_b32_e32 v52, v45
	v_lshl_add_u64 v[10:11], v[10:11], 0, s[46:47]
	s_cmp_eq_u32 s0, 0
	s_waitcnt vmcnt(3)
	v_pk_fma_f32 v[12:13], v[70:71], v[78:79], v[12:13] op_sel_hi:[0,1,1]
	v_pk_fma_f32 v[14:15], v[70:71], v[80:81], v[14:15] op_sel_hi:[0,1,1]
	s_waitcnt lgkmcnt(1)
	v_fmac_f32_e32 v21, v70, v54
	v_pk_fma_f32 v[12:13], v[62:63], v[30:31], v[12:13] op_sel_hi:[0,1,1]
	v_pk_fma_f32 v[14:15], v[62:63], v[46:47], v[14:15] op_sel_hi:[0,1,1]
	v_fmac_f32_e32 v21, v62, v55
	v_pk_fma_f32 v[12:13], v[64:65], v[22:23], v[12:13] op_sel_hi:[0,1,1]
	v_pk_fma_f32 v[14:15], v[64:65], v[38:39], v[14:15] op_sel_hi:[0,1,1]
	v_fmac_f32_e32 v21, v64, v56
	v_pk_fma_f32 v[12:13], v[66:67], v[32:33], v[12:13] op_sel_hi:[0,1,1]
	v_pk_fma_f32 v[14:15], v[66:67], v[48:49], v[14:15] op_sel_hi:[0,1,1]
	v_fmac_f32_e32 v21, v66, v57
	v_pk_fma_f32 v[12:13], v[68:69], v[24:25], v[12:13] op_sel_hi:[0,1,1]
	v_pk_fma_f32 v[14:15], v[68:69], v[40:41], v[14:15] op_sel_hi:[0,1,1]
	s_waitcnt lgkmcnt(0)
	v_fmac_f32_e32 v21, v68, v58
	s_waitcnt vmcnt(2)
	v_pk_fma_f32 v[12:13], v[72:73], v[34:35], v[12:13] op_sel_hi:[0,1,1]
	v_pk_fma_f32 v[14:15], v[72:73], v[50:51], v[14:15] op_sel_hi:[0,1,1]
	v_fmac_f32_e32 v21, v72, v59
	s_waitcnt vmcnt(1)
	v_pk_fma_f32 v[12:13], v[74:75], v[26:27], v[12:13] op_sel_hi:[0,1,1]
	v_pk_fma_f32 v[14:15], v[74:75], v[42:43], v[14:15] op_sel_hi:[0,1,1]
	v_fmac_f32_e32 v21, v74, v60
	s_waitcnt vmcnt(0)
	v_pk_fma_f32 v[12:13], v[76:77], v[36:37], v[12:13] op_sel_hi:[0,1,1]
	v_pk_fma_f32 v[14:15], v[76:77], v[52:53], v[14:15] op_sel_hi:[0,1,1]
	v_fmac_f32_e32 v21, v76, v61
	s_cbranch_scc0 .LBB0_34
	ds_write2st64_b32 v17, v12, v13 offset1:1
	ds_write2st64_b32 v17, v14, v15 offset0:2 offset1:3
	ds_write_b32 v17, v21 offset:1024
	s_waitcnt lgkmcnt(0)
	s_barrier
	s_and_saveexec_b64 s[46:47], s[40:41]
	s_cbranch_execz .LBB0_16
	s_lshl_b32 s50, s56, 6
	v_add_u32_e32 v10, s50, v2
	v_ashrrev_i32_e32 v11, 31, v10
	v_lshl_add_u64 v[10:11], v[10:11], 2, s[12:13]
	global_load_dword v21, v[10:11], off nt
	ds_read2st64_b32 v[10:11], v20 offset1:5
	ds_read2st64_b32 v[12:13], v20 offset0:10 offset1:15
	ds_read2st64_b32 v[14:15], v20 offset0:20 offset1:25
	ds_read2st64_b32 v[22:23], v20 offset0:30 offset1:35
	s_ashr_i32 s51, s50, 31
	s_waitcnt lgkmcnt(3)
	v_add_f32_e32 v10, 0, v10
	v_add_f32_e32 v10, v10, v11
	s_waitcnt lgkmcnt(2)
	v_add_f32_e32 v10, v10, v12
	v_add_f32_e32 v10, v10, v13
	s_waitcnt lgkmcnt(1)
	v_add_f32_e32 v10, v10, v14
	v_add_f32_e32 v10, v10, v15
	s_waitcnt lgkmcnt(0)
	v_add_f32_e32 v10, v10, v22
	v_add_f32_e32 v10, v10, v23
	s_waitcnt vmcnt(0)
	v_add_f32_e32 v12, v10, v21
	v_lshl_add_u64 v[10:11], s[50:51], 2, v[4:5]
	global_store_dword v[10:11], v12, off
	s_branch .LBB0_16

.LBB0_622:
	s_mul_hi_i32 s0, s40, 0x78787879
	s_lshr_b32 s2, s0, 31
	s_ashr_i32 s0, s0, 11
	s_add_i32 s0, s0, s2
	s_mulk_i32 s0, 0x1100
	s_sub_i32 s0, s40, s0
	s_cmpk_lt_i32 s0, 0x100
	s_cselect_b64 s[4:5], -1, 0
	s_and_b64 s[4:5], s[78:79], s[4:5]
	s_and_b64 vcc, exec, s[4:5]
	s_cbranch_vccnz .LBB0_621
	s_waitcnt vmcnt(0)
	v_lshl_add_u64 v[140:141], s[44:45], 0, v[194:195]
	v_add_co_u32_e32 v42, vcc, 0x4b438000, v140
	s_mov_b32 s0, 0x4b439000
	s_nop 0
	v_addc_co_u32_e32 v43, vcc, 0, v141, vcc
	v_add_co_u32_e32 v44, vcc, 0x53c38000, v140
	v_lshl_add_u64 v[62:63], s[46:47], 0, v[194:195]
	s_nop 0
	v_addc_co_u32_e32 v45, vcc, 0, v141, vcc
	v_add_co_u32_e32 v50, vcc, s0, v140
	s_mov_b32 s0, 0x53c39000
	s_nop 0
	v_addc_co_u32_e32 v51, vcc, 0, v141, vcc
	v_add_co_u32_e32 v52, vcc, s0, v140
	s_mov_b32 s0, 0x1bfb8000
	s_nop 0
	v_addc_co_u32_e32 v53, vcc, 0, v141, vcc
	global_load_dwordx4 v[126:129], v[42:43], off nt
	global_load_dwordx4 v[130:133], v[44:45], off nt
	global_load_dwordx4 v[82:85], v[42:43], off offset:1024 nt
	global_load_dwordx4 v[78:81], v[44:45], off offset:1024 nt
	global_load_dwordx4 v[118:121], v[42:43], off offset:2048 nt
	global_load_dwordx4 v[114:117], v[44:45], off offset:2048 nt
	global_load_dwordx4 v[70:73], v[42:43], off offset:3072 nt
	global_load_dwordx4 v[66:69], v[44:45], off offset:3072 nt
	global_load_dwordx4 v[90:93], v[50:51], off nt
	global_load_dwordx4 v[94:97], v[52:53], off nt
	global_load_dwordx4 v[46:49], v[50:51], off offset:1024 nt
	s_nop 0
	global_load_dwordx4 v[42:45], v[52:53], off offset:1024 nt
	global_load_dwordx4 v[106:109], v[50:51], off offset:2048 nt
	global_load_dwordx4 v[102:105], v[52:53], off offset:2048 nt
	global_load_dwordx4 v[58:61], v[50:51], off offset:3072 nt
	global_load_dwordx4 v[54:57], v[52:53], off offset:3072 nt
	v_add_co_u32_e32 v50, vcc, s0, v62
	s_mov_b32 s0, 0x225b8000
	s_nop 0
	v_addc_co_u32_e32 v51, vcc, 0, v63, vcc
	global_load_dwordx4 v[134:137], v[50:51], off nt
	v_add_co_u32_e32 v50, vcc, s0, v62
	s_mov_b32 s0, 0x247b8000
	s_nop 0
	v_addc_co_u32_e32 v51, vcc, 0, v63, vcc
	global_load_dwordx4 v[122:125], v[50:51], off nt
	v_add_co_u32_e32 v50, vcc, s0, v62
	s_mov_b32 s0, 0x2cfb8000
	s_nop 0
	v_addc_co_u32_e32 v51, vcc, 0, v63, vcc
	global_load_dwordx4 v[98:101], v[50:51], off nt
	v_add_co_u32_e32 v50, vcc, s0, v62
	s_mov_b32 s0, 0x1d0b8000
	s_nop 0
	v_addc_co_u32_e32 v51, vcc, 0, v63, vcc
	global_load_dwordx4 v[110:113], v[50:51], off nt
	v_add_co_u32_e32 v50, vcc, s0, v62
	s_mov_b32 s0, 0x236b8000
	s_nop 0
	v_addc_co_u32_e32 v51, vcc, 0, v63, vcc
	global_load_dwordx4 v[86:89], v[50:51], off nt
	v_add_co_u32_e32 v50, vcc, s0, v62
	s_mov_b32 s0, 0x258b8000
	s_nop 0
	v_addc_co_u32_e32 v51, vcc, 0, v63, vcc
	global_load_dwordx4 v[74:77], v[50:51], off nt
	v_add_co_u32_e32 v50, vcc, s0, v62
	s_mov_b32 s0, 0x2e0b8000
	s_nop 0
	v_addc_co_u32_e32 v51, vcc, 0, v63, vcc
	v_add_co_u32_e32 v62, vcc, s0, v62
	v_and_b32_e32 v143, 64, v215
	s_nop 0
	v_addc_co_u32_e32 v63, vcc, 0, v63, vcc
	v_xor_b32_e32 v142, 16, v215
	v_add_u32_e32 v143, 64, v143
	v_cmp_lt_i32_e32 vcc, v142, v143
	s_mov_b32 s0, 0x40a38000
	global_load_dwordx4 v[50:53], v[50:51], off nt
	v_cndmask_b32_e32 v142, v215, v142, vcc
	v_lshlrev_b32_e32 v146, 2, v142
	global_load_dwordx4 v[62:65], v[62:63], off nt
	v_lshl_add_u64 v[138:139], s[42:43], 0, v[194:195]
	s_waitcnt vmcnt(22)
	v_lshlrev_b32_e32 v148, 16, v133
	v_and_b32_e32 v149, 0xffff0000, v133
	v_lshlrev_b32_e32 v152, 16, v131
	v_and_b32_e32 v153, 0xffff0000, v131
	v_lshlrev_b32_e32 v144, 16, v129
	v_and_b32_e32 v145, 0xffff0000, v129
	v_lshlrev_b32_e32 v150, 16, v128
	v_and_b32_e32 v151, 0xffff0000, v128
	v_lshlrev_b32_e32 v128, 16, v132
	v_and_b32_e32 v129, 0xffff0000, v132
	v_pk_add_f32 v[128:129], v[150:151], v[128:129]
	v_pk_add_f32 v[144:145], v[144:145], v[148:149]
	s_waitcnt vmcnt(7)
	v_lshlrev_b32_e32 v132, 16, v136
	v_mul_f32_e32 v147, 0xbfb8aa3b, v132
	v_exp_f32_e32 v147, v147
	v_and_b32_e32 v133, 0xffff0000, v136
	v_lshlrev_b32_e32 v154, 16, v135
	v_and_b32_e32 v155, 0xffff0000, v135
	v_add_f32_e32 v147, 1.0, v147
	v_rcp_f32_e32 v150, v147
	v_mul_f32_e32 v147, 0xbfb8aa3b, v133
	v_exp_f32_e32 v147, v147
	v_and_b32_e32 v131, 0xffff0000, v134
	v_lshlrev_b32_e32 v142, 16, v137
	v_and_b32_e32 v143, 0xffff0000, v137
	v_add_f32_e32 v147, 1.0, v147
	v_rcp_f32_e32 v151, v147
	v_pk_mul_f32 v[136:137], v[128:129], v[128:129]
	v_pk_mul_f32 v[148:149], v[144:145], v[144:145]
	v_pk_mul_f32 v[132:133], v[150:151], v[132:133]
	v_lshlrev_b32_e32 v150, 16, v127
	v_and_b32_e32 v151, 0xffff0000, v127
	v_mul_f32_e32 v127, 0xbfb8aa3b, v154
	v_exp_f32_e32 v127, v127
	v_pk_add_f32 v[150:151], v[150:151], v[152:153]
	v_add_f32_e32 v127, 1.0, v127
	v_rcp_f32_e32 v156, v127
	v_mul_f32_e32 v127, 0xbfb8aa3b, v155
	v_exp_f32_e32 v127, v127
	v_pk_mul_f32 v[152:153], v[150:151], v[150:151]
	v_add_f32_e32 v127, 1.0, v127
	v_rcp_f32_e32 v157, v127
	v_and_b32_e32 v127, 0xffff0000, v130
	v_pk_mul_f32 v[154:155], v[156:157], v[154:155]
	v_lshlrev_b32_e32 v156, 16, v126
	v_and_b32_e32 v157, 0xffff0000, v126
	v_lshlrev_b32_e32 v126, 16, v130
	v_pk_add_f32 v[126:127], v[156:157], v[126:127]
	v_lshlrev_b32_e32 v130, 16, v134
	v_pk_mul_f32 v[134:135], v[126:127], v[126:127]
	v_mul_f32_e32 v147, 0xbfb8aa3b, v130
	v_add_f32_e32 v134, v134, v135
	v_add_f32_e32 v134, v152, v134
	v_add_f32_e32 v134, v153, v134
	v_add_f32_e32 v134, v136, v134
	v_add_f32_e32 v134, v137, v134
	v_add_f32_e32 v134, v148, v134
	v_add_f32_e32 v134, v149, v134
	v_exp_f32_e32 v147, v147
	s_nop 0
	v_add_f32_dpp v134, v134, v134 quad_perm:[1,0,3,2] row_mask:0xf bank_mask:0xf bound_ctrl:1
	v_add_f32_e32 v147, 1.0, v147
	s_nop 0
	v_add_f32_dpp v134, v134, v134 quad_perm:[2,3,0,1] row_mask:0xf bank_mask:0xf bound_ctrl:1
	v_rcp_f32_e32 v156, v147
	v_mul_f32_e32 v147, 0xbfb8aa3b, v131
	v_add_f32_dpp v134, v134, v134 row_half_mirror row_mask:0xf bank_mask:0xf bound_ctrl:1
	v_exp_f32_e32 v147, v147
	s_nop 0
	v_add_f32_dpp v134, v134, v134 row_mirror row_mask:0xf bank_mask:0xf bound_ctrl:1
	v_fmamk_f32 v134, v134, 0x3c000000, v202
	v_cmp_gt_f32_e32 vcc, s25, v134
	v_mul_f32_e32 v135, 0x4f800000, v134
	v_add_f32_e32 v147, 1.0, v147
	v_cndmask_b32_e32 v134, v134, v135, vcc
	v_sqrt_f32_e32 v135, v134
	v_rcp_f32_e32 v157, v147
	v_add_u32_e32 v136, -1, v135
	v_fma_f32 v137, -v136, v135, v134
	v_cmp_ge_f32_e64 s[38:39], 0, v137
	v_add_u32_e32 v137, 1, v135
	v_pk_mul_f32 v[130:131], v[156:157], v[130:131]
	v_cndmask_b32_e64 v136, v135, v136, s[38:39]
	v_fma_f32 v135, -v137, v135, v134
	v_cmp_lt_f32_e64 s[38:39], 0, v135
	s_nop 1
	v_cndmask_b32_e64 v135, v136, v137, s[38:39]
	v_mul_f32_e32 v136, 0x37800000, v135
	v_cndmask_b32_e32 v135, v135, v136, vcc
	v_cmp_class_f32_e32 vcc, v134, v203
	s_nop 1
	v_cndmask_b32_e32 v134, v135, v134, vcc
	v_div_scale_f32 v135, s[4:5], v134, v134, 1.0
	v_rcp_f32_e32 v136, v135
	s_nop 0
	v_fma_f32 v137, -v135, v136, 1.0
	v_fmac_f32_e32 v136, v137, v136
	v_div_scale_f32 v137, vcc, 1.0, v134, 1.0
	v_mul_f32_e32 v147, v137, v136
	v_fma_f32 v148, -v135, v147, v137
	v_fmac_f32_e32 v147, v148, v136
	v_fma_f32 v135, -v135, v147, v137
	v_div_fmas_f32 v135, v135, v136, v147
	v_div_fixup_f32 v134, v135, v134, 1.0
	v_pk_mul_f32 v[128:129], v[128:129], v[134:135] op_sel_hi:[1,0]
	v_pk_mul_f32 v[126:127], v[126:127], v[134:135] op_sel_hi:[1,0]
	v_pk_mul_f32 v[128:129], v[2:3], v[128:129]
	v_pk_mul_f32 v[126:127], v[6:7], v[126:127]
	v_pk_mul_f32 v[132:133], v[132:133], v[128:129]
	v_mul_f32_e32 v128, 0xbfb8aa3b, v142
	v_mul_f32_e32 v129, 0xbfb8aa3b, v143
	v_exp_f32_e32 v128, v128
	v_exp_f32_e32 v129, v129
	v_lshlrev_b32_e32 v136, 16, v115
	v_and_b32_e32 v137, 0xffff0000, v115
	v_add_f32_e32 v128, 1.0, v128
	v_add_f32_e32 v129, 1.0, v129
	v_rcp_f32_e32 v128, v128
	v_rcp_f32_e32 v129, v129
	v_pk_mul_f32 v[126:127], v[130:131], v[126:127]
	v_pk_mul_f32 v[130:131], v[150:151], v[134:135] op_sel_hi:[1,0]
	v_pk_mul_f32 v[134:135], v[144:145], v[134:135] op_sel_hi:[1,0]
	v_pk_mul_f32 v[128:129], v[128:129], v[142:143]
	s_waitcnt vmcnt(6)
	v_lshlrev_b32_e32 v142, 16, v123
	v_mul_f32_e32 v115, 0xbfb8aa3b, v142
	v_exp_f32_e32 v115, v115
	v_pk_mul_f32 v[130:131], v[8:9], v[130:131]
	v_pk_mul_f32 v[134:135], v[4:5], v[134:135]
	v_pk_mul_f32 v[130:131], v[154:155], v[130:131]
	v_pk_mul_f32 v[134:135], v[128:129], v[134:135]
	v_cvt_pk_bf16_f32 v128, v126, v127
	v_add_co_u32_e32 v126, vcc, s0, v140
	v_cvt_pk_bf16_f32 v129, v130, v131
	v_cvt_pk_bf16_f32 v130, v132, v133
	v_cvt_pk_bf16_f32 v131, v134, v135
	v_addc_co_u32_e32 v127, vcc, 0, v141, vcc
	global_store_dwordx4 v[126:127], v[128:131], off
	v_lshlrev_b32_e32 v132, 16, v117
	v_and_b32_e32 v133, 0xffff0000, v117
	v_lshlrev_b32_e32 v130, 16, v121
	v_and_b32_e32 v131, 0xffff0000, v121
	v_lshlrev_b32_e32 v134, 16, v120
	v_and_b32_e32 v135, 0xffff0000, v120
	v_lshlrev_b32_e32 v120, 16, v116
	v_and_b32_e32 v121, 0xffff0000, v116
	v_lshlrev_b32_e32 v116, 16, v124
	v_and_b32_e32 v117, 0xffff0000, v124
	v_and_b32_e32 v143, 0xffff0000, v123
	v_add_f32_e32 v115, 1.0, v115
	v_pk_add_f32 v[120:121], v[134:135], v[120:121]
	v_mul_f32_e32 v134, 0xbfb8aa3b, v116
	v_mul_f32_e32 v135, 0xbfb8aa3b, v117
	v_rcp_f32_e32 v144, v115
	v_mul_f32_e32 v115, 0xbfb8aa3b, v143
	v_exp_f32_e32 v134, v134
	v_exp_f32_e32 v135, v135
	v_exp_f32_e32 v115, v115
	v_lshlrev_b32_e32 v128, 16, v125
	v_add_f32_e32 v134, 1.0, v134
	v_add_f32_e32 v135, 1.0, v135
	v_add_f32_e32 v115, 1.0, v115
	v_rcp_f32_e32 v134, v134
	v_rcp_f32_e32 v135, v135
	v_rcp_f32_e32 v145, v115
	v_and_b32_e32 v115, 0xffff0000, v122
	v_and_b32_e32 v129, 0xffff0000, v125
	v_pk_mul_f32 v[116:117], v[134:135], v[116:117]
	v_lshlrev_b32_e32 v134, 16, v119
	v_and_b32_e32 v135, 0xffff0000, v119
	v_pk_mul_f32 v[142:143], v[144:145], v[142:143]
	v_lshlrev_b32_e32 v144, 16, v118
	v_and_b32_e32 v145, 0xffff0000, v118
	v_lshlrev_b32_e32 v118, 16, v114
	v_and_b32_e32 v119, 0xffff0000, v114
	v_pk_add_f32 v[118:119], v[144:145], v[118:119]
	v_pk_add_f32 v[134:135], v[134:135], v[136:137]
	v_lshlrev_b32_e32 v114, 16, v122
	v_pk_mul_f32 v[122:123], v[118:119], v[118:119]
	v_pk_mul_f32 v[136:137], v[134:135], v[134:135]
	v_add_f32_e32 v122, v122, v123
	v_add_f32_e32 v122, v136, v122
	v_pk_mul_f32 v[124:125], v[120:121], v[120:121]
	v_add_f32_e32 v122, v137, v122
	v_pk_add_f32 v[130:131], v[130:131], v[132:133]
	v_add_f32_e32 v122, v124, v122
	v_pk_mul_f32 v[132:133], v[130:131], v[130:131]
	v_add_f32_e32 v122, v125, v122
	v_add_f32_e32 v122, v132, v122
	v_add_f32_e32 v122, v133, v122
	v_mul_f32_e32 v144, 0xbfb8aa3b, v114
	v_mul_f32_e32 v145, 0xbfb8aa3b, v115
	v_add_f32_dpp v122, v122, v122 quad_perm:[1,0,3,2] row_mask:0xf bank_mask:0xf bound_ctrl:1
	v_exp_f32_e32 v144, v144
	v_exp_f32_e32 v145, v145
	v_add_f32_dpp v122, v122, v122 quad_perm:[2,3,0,1] row_mask:0xf bank_mask:0xf bound_ctrl:1
	s_mov_b32 s0, 0x40a39000
	v_add_f32_e32 v144, 1.0, v144
	v_add_f32_dpp v122, v122, v122 row_half_mirror row_mask:0xf bank_mask:0xf bound_ctrl:1
	v_add_f32_e32 v145, 1.0, v145
	v_rcp_f32_e32 v144, v144
	v_add_f32_dpp v122, v122, v122 row_mirror row_mask:0xf bank_mask:0xf bound_ctrl:1
	ds_bpermute_b32 v123, v146, v122
	v_rcp_f32_e32 v145, v145
	s_waitcnt lgkmcnt(0)
	v_add_f32_e32 v122, v122, v123
	v_fmamk_f32 v122, v122, 0x3b800000, v202
	v_cmp_gt_f32_e32 vcc, s25, v122
	v_mul_f32_e32 v123, 0x4f800000, v122
	v_pk_mul_f32 v[114:115], v[144:145], v[114:115]
	v_cndmask_b32_e32 v122, v122, v123, vcc
	v_sqrt_f32_e32 v123, v122
	s_nop 0
	v_add_u32_e32 v124, -1, v123
	v_fma_f32 v125, -v124, v123, v122
	v_cmp_ge_f32_e64 s[38:39], 0, v125
	v_add_u32_e32 v125, 1, v123
	s_nop 0
	v_cndmask_b32_e64 v124, v123, v124, s[38:39]
	v_fma_f32 v123, -v125, v123, v122
	v_cmp_lt_f32_e64 s[38:39], 0, v123
	s_nop 1
	v_cndmask_b32_e64 v123, v124, v125, s[38:39]
	v_mul_f32_e32 v124, 0x37800000, v123
	v_cndmask_b32_e32 v123, v123, v124, vcc
	v_cmp_class_f32_e32 vcc, v122, v203
	s_nop 1
	v_cndmask_b32_e32 v122, v123, v122, vcc
	v_div_scale_f32 v123, s[4:5], v122, v122, 1.0
	v_rcp_f32_e32 v124, v123
	s_nop 0
	v_fma_f32 v125, -v123, v124, 1.0
	v_fmac_f32_e32 v124, v125, v124
	v_div_scale_f32 v125, vcc, 1.0, v122, 1.0
	v_mul_f32_e32 v132, v125, v124
	v_fma_f32 v133, -v123, v132, v125
	v_fmac_f32_e32 v132, v133, v124
	v_fma_f32 v123, -v123, v132, v125
	v_div_fmas_f32 v123, v123, v124, v132
	v_div_fixup_f32 v122, v123, v122, 1.0
	v_pk_mul_f32 v[120:121], v[120:121], v[122:123] op_sel_hi:[1,0]
	v_pk_mul_f32 v[118:119], v[118:119], v[122:123] op_sel_hi:[1,0]
	v_pk_mul_f32 v[120:121], v[10:11], v[120:121]
	v_pk_mul_f32 v[118:119], v[14:15], v[118:119]
	v_pk_mul_f32 v[116:117], v[116:117], v[120:121]
	v_mul_f32_e32 v120, 0xbfb8aa3b, v128
	v_mul_f32_e32 v121, 0xbfb8aa3b, v129
	v_exp_f32_e32 v120, v120
	v_exp_f32_e32 v121, v121
	v_pk_mul_f32 v[114:115], v[114:115], v[118:119]
	v_pk_mul_f32 v[118:119], v[134:135], v[122:123] op_sel_hi:[1,0]
	v_add_f32_e32 v120, 1.0, v120
	v_add_f32_e32 v121, 1.0, v121
	v_rcp_f32_e32 v120, v120
	v_rcp_f32_e32 v121, v121
	v_pk_mul_f32 v[122:123], v[130:131], v[122:123] op_sel_hi:[1,0]
	v_pk_mul_f32 v[118:119], v[16:17], v[118:119]
	v_pk_mul_f32 v[122:123], v[12:13], v[122:123]
	v_pk_mul_f32 v[120:121], v[120:121], v[128:129]
	v_pk_mul_f32 v[118:119], v[142:143], v[118:119]
	v_pk_mul_f32 v[120:121], v[120:121], v[122:123]
	v_cvt_pk_bf16_f32 v114, v114, v115
	v_cvt_pk_bf16_f32 v115, v118, v119
	v_cvt_pk_bf16_f32 v116, v116, v117
	v_cvt_pk_bf16_f32 v117, v120, v121
	global_store_dwordx4 v[126:127], v[114:117], off offset:2048
	v_lshlrev_b32_e32 v118, 16, v105
	v_and_b32_e32 v119, 0xffff0000, v105
	v_lshlrev_b32_e32 v116, 16, v109
	v_and_b32_e32 v117, 0xffff0000, v109
	v_pk_add_f32 v[116:117], v[116:117], v[118:119]
	v_lshlrev_b32_e32 v118, 16, v108
	v_and_b32_e32 v119, 0xffff0000, v108
	v_lshlrev_b32_e32 v108, 16, v104
	v_and_b32_e32 v109, 0xffff0000, v104
	s_waitcnt vmcnt(6)
	v_lshlrev_b32_e32 v104, 16, v112
	v_and_b32_e32 v105, 0xffff0000, v112
	v_lshlrev_b32_e32 v114, 16, v113
	v_and_b32_e32 v115, 0xffff0000, v113
	v_mul_f32_e32 v112, 0xbfb8aa3b, v104
	v_mul_f32_e32 v113, 0xbfb8aa3b, v105
	v_exp_f32_e32 v112, v112
	v_exp_f32_e32 v113, v113
	v_lshlrev_b32_e32 v120, 16, v111
	v_pk_add_f32 v[108:109], v[118:119], v[108:109]
	v_add_f32_e32 v112, 1.0, v112
	v_add_f32_e32 v113, 1.0, v113
	v_lshlrev_b32_e32 v118, 16, v103
	v_and_b32_e32 v119, 0xffff0000, v103
	v_mul_f32_e32 v103, 0xbfb8aa3b, v120
	v_rcp_f32_e32 v112, v112
	v_rcp_f32_e32 v113, v113
	v_exp_f32_e32 v103, v103
	v_and_b32_e32 v121, 0xffff0000, v111
	v_pk_mul_f32 v[104:105], v[112:113], v[104:105]
	v_lshlrev_b32_e32 v112, 16, v107
	v_and_b32_e32 v113, 0xffff0000, v107
	v_add_f32_e32 v103, 1.0, v103
	v_pk_add_f32 v[112:113], v[112:113], v[118:119]
	v_rcp_f32_e32 v118, v103
	v_mul_f32_e32 v103, 0xbfb8aa3b, v121
	v_exp_f32_e32 v103, v103
	v_and_b32_e32 v107, 0xffff0000, v102
	v_add_f32_e32 v103, 1.0, v103
	v_rcp_f32_e32 v119, v103
	v_and_b32_e32 v103, 0xffff0000, v110
	v_mul_f32_e32 v111, 0xbfb8aa3b, v103
	v_exp_f32_e32 v111, v111
	v_pk_mul_f32 v[118:119], v[118:119], v[120:121]
	v_lshlrev_b32_e32 v120, 16, v106
	v_and_b32_e32 v121, 0xffff0000, v106
	v_lshlrev_b32_e32 v106, 16, v102
	v_pk_add_f32 v[106:107], v[120:121], v[106:107]
	v_lshlrev_b32_e32 v102, 16, v110
	v_add_f32_e32 v110, 0, v106
	v_add_f32_e32 v120, v107, v110
	v_mul_f32_e32 v110, 0xbfb8aa3b, v102
	v_exp_f32_e32 v110, v110
	v_add_f32_e32 v111, 1.0, v111
	v_rcp_f32_e32 v111, v111
	v_add_f32_e32 v110, 1.0, v110
	v_rcp_f32_e32 v110, v110
	s_nop 0
	v_pk_mul_f32 v[102:103], v[110:111], v[102:103]
	v_add_f32_e32 v110, v112, v120
	v_add_f32_e32 v110, v113, v110
	v_add_f32_e32 v110, v108, v110
	v_add_f32_e32 v110, v109, v110
	v_add_f32_e32 v110, v116, v110
	v_add_f32_e32 v110, v117, v110
	s_nop 1
	v_add_f32_dpp v110, v110, v110 quad_perm:[1,0,3,2] row_mask:0xf bank_mask:0xf bound_ctrl:1
	s_nop 1
	v_add_f32_dpp v110, v110, v110 quad_perm:[2,3,0,1] row_mask:0xf bank_mask:0xf bound_ctrl:1
	s_nop 1
	v_add_f32_dpp v110, v110, v110 row_half_mirror row_mask:0xf bank_mask:0xf bound_ctrl:1
	s_nop 1
	v_add_f32_dpp v110, v110, v110 row_mirror row_mask:0xf bank_mask:0xf bound_ctrl:1
	ds_bpermute_b32 v111, v146, v110
	s_waitcnt lgkmcnt(0)
	v_add_f32_e32 v110, v110, v111
	v_mul_f32_e32 v110, 0x3b800000, v110
	v_pk_add_f32 v[106:107], v[106:107], v[110:111] op_sel_hi:[1,0] neg_lo:[0,1] neg_hi:[0,1]
	v_pk_add_f32 v[112:113], v[112:113], v[110:111] op_sel_hi:[1,0] neg_lo:[0,1] neg_hi:[0,1]
	v_pk_mul_f32 v[120:121], v[106:107], v[106:107]
	v_pk_mul_f32 v[122:123], v[112:113], v[112:113]
	v_add_f32_e32 v120, v120, v121
	v_pk_add_f32 v[108:109], v[108:109], v[110:111] op_sel_hi:[1,0] neg_lo:[0,1] neg_hi:[0,1]
	v_add_f32_e32 v120, v122, v120
	v_pk_mul_f32 v[124:125], v[108:109], v[108:109]
	v_add_f32_e32 v120, v123, v120
	v_pk_add_f32 v[110:111], v[116:117], v[110:111] op_sel_hi:[1,0] neg_lo:[0,1] neg_hi:[0,1]
	v_add_f32_e32 v120, v124, v120
	v_pk_mul_f32 v[116:117], v[110:111], v[110:111]
	v_add_f32_e32 v120, v125, v120
	v_add_f32_e32 v116, v116, v120
	v_add_f32_e32 v116, v117, v116
	s_nop 1
	v_add_f32_dpp v116, v116, v116 quad_perm:[1,0,3,2] row_mask:0xf bank_mask:0xf bound_ctrl:1
	s_nop 1
	v_add_f32_dpp v116, v116, v116 quad_perm:[2,3,0,1] row_mask:0xf bank_mask:0xf bound_ctrl:1
	s_nop 1
	v_add_f32_dpp v116, v116, v116 row_half_mirror row_mask:0xf bank_mask:0xf bound_ctrl:1
	s_nop 1
	v_add_f32_dpp v116, v116, v116 row_mirror row_mask:0xf bank_mask:0xf bound_ctrl:1
	ds_bpermute_b32 v117, v146, v116
	s_waitcnt lgkmcnt(0)
	v_add_f32_e32 v116, v116, v117
	v_fmamk_f32 v116, v116, 0x3b800000, v202
	v_cmp_gt_f32_e32 vcc, s25, v116
	v_mul_f32_e32 v117, 0x4f800000, v116
	s_nop 0
	v_cndmask_b32_e32 v116, v116, v117, vcc
	v_sqrt_f32_e32 v117, v116
	s_nop 0
	v_add_u32_e32 v120, -1, v117
	v_fma_f32 v121, -v120, v117, v116
	v_cmp_ge_f32_e64 s[38:39], 0, v121
	v_add_u32_e32 v121, 1, v117
	s_nop 0
	v_cndmask_b32_e64 v120, v117, v120, s[38:39]
	v_fma_f32 v117, -v121, v117, v116
	v_cmp_lt_f32_e64 s[38:39], 0, v117
	s_nop 1
	v_cndmask_b32_e64 v117, v120, v121, s[38:39]
	v_mul_f32_e32 v120, 0x37800000, v117
	v_cndmask_b32_e32 v117, v117, v120, vcc
	v_cmp_class_f32_e32 vcc, v116, v203
	s_nop 1
	v_cndmask_b32_e32 v116, v117, v116, vcc
	v_div_scale_f32 v117, s[4:5], v116, v116, 1.0
	v_rcp_f32_e32 v120, v117
	s_nop 0
	v_fma_f32 v121, -v117, v120, 1.0
	v_fmac_f32_e32 v120, v121, v120
	v_div_scale_f32 v121, vcc, 1.0, v116, 1.0
	v_mul_f32_e32 v122, v121, v120
	v_fma_f32 v123, -v117, v122, v121
	v_fmac_f32_e32 v122, v123, v120
	v_fma_f32 v117, -v117, v122, v121
	v_div_fmas_f32 v117, v117, v120, v122
	v_div_fixup_f32 v116, v117, v116, 1.0
	v_pk_mul_f32 v[108:109], v[108:109], v[116:117] op_sel_hi:[1,0]
	v_pk_mul_f32 v[106:107], v[106:107], v[116:117] op_sel_hi:[1,0]
	v_pk_mul_f32 v[108:109], v[18:19], v[108:109]
	v_pk_mul_f32 v[106:107], v[22:23], v[106:107]
	v_pk_mul_f32 v[108:109], v[104:105], v[108:109]
	v_mul_f32_e32 v104, 0xbfb8aa3b, v114
	v_mul_f32_e32 v105, 0xbfb8aa3b, v115
	v_exp_f32_e32 v104, v104
	v_exp_f32_e32 v105, v105
	v_pk_mul_f32 v[102:103], v[102:103], v[106:107]
	v_pk_mul_f32 v[106:107], v[112:113], v[116:117] op_sel_hi:[1,0]
	v_add_f32_e32 v104, 1.0, v104
	v_add_f32_e32 v105, 1.0, v105
	v_rcp_f32_e32 v104, v104
	v_rcp_f32_e32 v105, v105
	v_pk_mul_f32 v[110:111], v[110:111], v[116:117] op_sel_hi:[1,0]
	v_pk_mul_f32 v[106:107], v[24:25], v[106:107]
	v_pk_mul_f32 v[110:111], v[20:21], v[110:111]
	v_pk_mul_f32 v[104:105], v[104:105], v[114:115]
	v_pk_mul_f32 v[106:107], v[118:119], v[106:107]
	v_pk_mul_f32 v[110:111], v[104:105], v[110:111]
	v_cvt_pk_bf16_f32 v104, v102, v103
	v_add_co_u32_e32 v102, vcc, s0, v140
	v_cvt_pk_bf16_f32 v105, v106, v107
	v_cvt_pk_bf16_f32 v106, v108, v109
	v_cvt_pk_bf16_f32 v107, v110, v111
	v_addc_co_u32_e32 v103, vcc, 0, v141, vcc
	global_store_dwordx4 v[102:103], v[104:107], off offset:2048
	v_lshlrev_b32_e32 v108, 16, v98
	v_and_b32_e32 v109, 0xffff0000, v98
	v_lshlrev_b32_e32 v104, 16, v90
	v_and_b32_e32 v105, 0xffff0000, v90
	v_lshlrev_b32_e32 v106, 16, v94
	v_and_b32_e32 v107, 0xffff0000, v94
	v_pk_add_f32 v[104:105], v[104:105], v[106:107]
	s_mov_b32 s0, 0x49238000
	v_pk_fma_f32 v[104:105], v[30:31], v[108:109], v[104:105]
	s_nop 0
	v_mul_f32_e32 v90, 0x3d372713, v104
	v_mul_f32_e32 v90, v104, v90
	v_fma_f32 v90, v104, v90, v104
	v_mul_f32_e32 v90, 0x3f4c422a, v90
	v_add_f32_e32 v90, v90, v90
	v_mul_f32_e32 v90, 0x3fb8aa3b, v90
	v_exp_f32_e32 v106, v90
	v_mul_f32_e32 v90, 0x3d372713, v105
	v_mul_f32_e32 v90, v105, v90
	v_fma_f32 v90, v105, v90, v105
	v_mul_f32_e32 v90, 0x3f4c422a, v90
	v_add_f32_e32 v90, v90, v90
	v_mul_f32_e32 v90, 0x3fb8aa3b, v90
	v_exp_f32_e32 v107, v90
	v_pk_mul_f32 v[104:105], v[104:105], 0.5 op_sel_hi:[1,0]
	v_pk_add_f32 v[106:107], v[106:107], 1.0 op_sel_hi:[1,0]
	s_nop 0
	v_div_scale_f32 v90, s[4:5], v107, v107, 2.0
	v_rcp_f32_e32 v94, v90
	s_nop 0
	v_fma_f32 v98, -v90, v94, 1.0
	v_fmac_f32_e32 v94, v98, v94
	v_div_scale_f32 v98, vcc, 2.0, v107, 2.0
	v_mul_f32_e32 v108, v98, v94
	v_fma_f32 v109, -v90, v108, v98
	v_fmac_f32_e32 v108, v109, v94
	v_fma_f32 v90, -v90, v108, v98
	v_div_fmas_f32 v90, v90, v94, v108
	v_div_fixup_f32 v107, v90, v107, 2.0
	v_div_scale_f32 v90, s[4:5], v106, v106, 2.0
	v_rcp_f32_e32 v94, v90
	s_nop 0
	v_fma_f32 v98, -v90, v94, 1.0
	v_fmac_f32_e32 v94, v98, v94
	v_div_scale_f32 v98, vcc, 2.0, v106, 2.0
	v_mul_f32_e32 v108, v98, v94
	v_fma_f32 v109, -v90, v108, v98
	v_fmac_f32_e32 v108, v109, v94
	v_fma_f32 v90, -v90, v108, v98
	v_div_fmas_f32 v90, v90, v94, v108
	v_div_fixup_f32 v106, v90, v106, 2.0
	v_lshlrev_b32_e32 v90, 16, v91
	v_and_b32_e32 v91, 0xffff0000, v91
	v_lshlrev_b32_e32 v94, 16, v95
	v_and_b32_e32 v95, 0xffff0000, v95
	v_lshlrev_b32_e32 v98, 16, v99
	v_and_b32_e32 v99, 0xffff0000, v99
	v_pk_add_f32 v[90:91], v[90:91], v[94:95]
	v_pk_add_f32 v[106:107], v[106:107], 1.0 op_sel_hi:[1,0] neg_lo:[1,0] neg_hi:[1,0]
	v_pk_fma_f32 v[90:91], v[32:33], v[98:99], v[90:91]
	v_pk_add_f32 v[106:107], v[106:107], 1.0 op_sel_hi:[1,0]
	v_mul_f32_e32 v94, 0x3d372713, v90
	v_mul_f32_e32 v95, 0x3d372713, v91
	v_mul_f32_e32 v94, v90, v94
	v_mul_f32_e32 v95, v91, v95
	v_fma_f32 v94, v90, v94, v90
	v_fma_f32 v95, v91, v95, v91
	v_mul_f32_e32 v94, 0x3f4c422a, v94
	v_mul_f32_e32 v95, 0x3f4c422a, v95
	v_add_f32_e32 v94, v94, v94
	v_add_f32_e32 v95, v95, v95
	v_mul_f32_e32 v94, 0x3fb8aa3b, v94
	v_mul_f32_e32 v95, 0x3fb8aa3b, v95
	v_exp_f32_e32 v94, v94
	v_exp_f32_e32 v95, v95
	v_pk_mul_f32 v[104:105], v[104:105], v[106:107]
	v_pk_mul_f32 v[90:91], v[90:91], 0.5 op_sel_hi:[1,0]
	v_pk_add_f32 v[94:95], v[94:95], 1.0 op_sel_hi:[1,0]
	s_nop 0
	v_div_scale_f32 v98, s[4:5], v95, v95, 2.0
	v_rcp_f32_e32 v99, v98
	s_nop 0
	v_fma_f32 v106, -v98, v99, 1.0
	v_fmac_f32_e32 v99, v106, v99
	v_div_scale_f32 v106, vcc, 2.0, v95, 2.0
	v_mul_f32_e32 v107, v106, v99
	v_fma_f32 v108, -v98, v107, v106
	v_fmac_f32_e32 v107, v108, v99
	v_fma_f32 v98, -v98, v107, v106
	v_div_fmas_f32 v98, v98, v99, v107
	v_div_fixup_f32 v95, v98, v95, 2.0
	v_div_scale_f32 v98, s[4:5], v94, v94, 2.0
	v_rcp_f32_e32 v99, v98
	s_nop 0
	v_fma_f32 v106, -v98, v99, 1.0
	v_fmac_f32_e32 v99, v106, v99
	v_div_scale_f32 v106, vcc, 2.0, v94, 2.0
	v_mul_f32_e32 v107, v106, v99
	v_fma_f32 v108, -v98, v107, v106
	v_fmac_f32_e32 v107, v108, v99
	v_fma_f32 v98, -v98, v107, v106
	v_div_fmas_f32 v98, v98, v99, v107
	v_div_fixup_f32 v94, v98, v94, 2.0
	v_pk_add_f32 v[94:95], v[94:95], 1.0 op_sel_hi:[1,0] neg_lo:[1,0] neg_hi:[1,0]
	v_lshlrev_b32_e32 v98, 16, v96
	v_pk_add_f32 v[94:95], v[94:95], 1.0 op_sel_hi:[1,0]
	v_and_b32_e32 v99, 0xffff0000, v96
	v_pk_mul_f32 v[90:91], v[90:91], v[94:95]
	v_lshlrev_b32_e32 v94, 16, v92
	v_and_b32_e32 v95, 0xffff0000, v92
	v_lshlrev_b32_e32 v106, 16, v100
	v_and_b32_e32 v107, 0xffff0000, v100
	v_pk_add_f32 v[94:95], v[94:95], v[98:99]
	s_nop 0
	v_pk_fma_f32 v[94:95], v[26:27], v[106:107], v[94:95]
	s_nop 0
	v_mul_f32_e32 v92, 0x3d372713, v94
	v_mul_f32_e32 v92, v94, v92
	v_fma_f32 v92, v94, v92, v94
	v_mul_f32_e32 v92, 0x3f4c422a, v92
	v_add_f32_e32 v92, v92, v92
	v_mul_f32_e32 v92, 0x3fb8aa3b, v92
	v_exp_f32_e32 v98, v92
	v_mul_f32_e32 v92, 0x3d372713, v95
	v_mul_f32_e32 v92, v95, v92
	v_fma_f32 v92, v95, v92, v95
	v_mul_f32_e32 v92, 0x3f4c422a, v92
	v_add_f32_e32 v92, v92, v92
	v_mul_f32_e32 v92, 0x3fb8aa3b, v92
	v_exp_f32_e32 v99, v92
	v_pk_mul_f32 v[94:95], v[94:95], 0.5 op_sel_hi:[1,0]
	v_pk_add_f32 v[98:99], v[98:99], 1.0 op_sel_hi:[1,0]
	s_nop 0
	v_div_scale_f32 v92, s[4:5], v99, v99, 2.0
	v_rcp_f32_e32 v96, v92
	s_nop 0
	v_fma_f32 v100, -v92, v96, 1.0
	v_fmac_f32_e32 v96, v100, v96
	v_div_scale_f32 v100, vcc, 2.0, v99, 2.0
	v_mul_f32_e32 v106, v100, v96
	v_fma_f32 v107, -v92, v106, v100
	v_fmac_f32_e32 v106, v107, v96
	v_fma_f32 v92, -v92, v106, v100
	v_div_fmas_f32 v92, v92, v96, v106
	v_div_fixup_f32 v99, v92, v99, 2.0
	v_div_scale_f32 v92, s[4:5], v98, v98, 2.0
	v_rcp_f32_e32 v96, v92
	s_nop 0
	v_fma_f32 v100, -v92, v96, 1.0
	v_fmac_f32_e32 v96, v100, v96
	v_div_scale_f32 v100, vcc, 2.0, v98, 2.0
	v_mul_f32_e32 v106, v100, v96
	v_fma_f32 v107, -v92, v106, v100
	v_fmac_f32_e32 v106, v107, v96
	v_fma_f32 v92, -v92, v106, v100
	v_div_fmas_f32 v92, v92, v96, v106
	v_div_fixup_f32 v98, v92, v98, 2.0
	v_pk_add_f32 v[98:99], v[98:99], 1.0 op_sel_hi:[1,0] neg_lo:[1,0] neg_hi:[1,0]
	v_lshlrev_b32_e32 v92, 16, v93
	v_pk_add_f32 v[98:99], v[98:99], 1.0 op_sel_hi:[1,0]
	v_and_b32_e32 v93, 0xffff0000, v93
	v_lshlrev_b32_e32 v96, 16, v97
	v_and_b32_e32 v97, 0xffff0000, v97
	v_pk_mul_f32 v[94:95], v[94:95], v[98:99]
	v_lshlrev_b32_e32 v98, 16, v101
	v_and_b32_e32 v99, 0xffff0000, v101
	v_pk_add_f32 v[92:93], v[92:93], v[96:97]
	v_cvt_pk_bf16_f32 v94, v94, v95
	v_pk_fma_f32 v[92:93], v[28:29], v[98:99], v[92:93]
	s_nop 0
	v_mul_f32_e32 v96, 0x3d372713, v92
	v_mul_f32_e32 v97, 0x3d372713, v93
	v_mul_f32_e32 v96, v92, v96
	v_mul_f32_e32 v97, v93, v97
	v_fma_f32 v96, v92, v96, v92
	v_fma_f32 v97, v93, v97, v93
	v_mul_f32_e32 v96, 0x3f4c422a, v96
	v_mul_f32_e32 v97, 0x3f4c422a, v97
	v_add_f32_e32 v96, v96, v96
	v_add_f32_e32 v97, v97, v97
	v_mul_f32_e32 v96, 0x3fb8aa3b, v96
	v_mul_f32_e32 v97, 0x3fb8aa3b, v97
	v_exp_f32_e32 v96, v96
	v_exp_f32_e32 v97, v97
	v_pk_mul_f32 v[92:93], v[92:93], 0.5 op_sel_hi:[1,0]
	v_pk_add_f32 v[96:97], v[96:97], 1.0 op_sel_hi:[1,0]
	s_nop 0
	v_div_scale_f32 v98, s[4:5], v97, v97, 2.0
	v_rcp_f32_e32 v99, v98
	s_nop 0
	v_fma_f32 v100, -v98, v99, 1.0
	v_fmac_f32_e32 v99, v100, v99
	v_div_scale_f32 v100, vcc, 2.0, v97, 2.0
	v_mul_f32_e32 v101, v100, v99
	v_fma_f32 v106, -v98, v101, v100
	v_fmac_f32_e32 v101, v106, v99
	v_fma_f32 v98, -v98, v101, v100
	v_div_fmas_f32 v98, v98, v99, v101
	v_div_fixup_f32 v97, v98, v97, 2.0
	v_div_scale_f32 v98, s[4:5], v96, v96, 2.0
	v_rcp_f32_e32 v99, v98
	s_nop 0
	v_fma_f32 v100, -v98, v99, 1.0
	v_fmac_f32_e32 v99, v100, v99
	v_div_scale_f32 v100, vcc, 2.0, v96, 2.0
	v_mul_f32_e32 v101, v100, v99
	v_fma_f32 v106, -v98, v101, v100
	v_fmac_f32_e32 v101, v106, v99
	v_fma_f32 v98, -v98, v101, v100
	v_div_fmas_f32 v98, v98, v99, v101
	v_div_fixup_f32 v96, v98, v96, 2.0
	v_pk_add_f32 v[96:97], v[96:97], 1.0 op_sel_hi:[1,0] neg_lo:[1,0] neg_hi:[1,0]
	v_lshlrev_b32_e32 v100, 16, v79
	v_pk_add_f32 v[96:97], v[96:97], 1.0 op_sel_hi:[1,0]
	v_and_b32_e32 v101, 0xffff0000, v79
	v_pk_mul_f32 v[96:97], v[92:93], v[96:97]
	v_cvt_pk_bf16_f32 v92, v104, v105
	s_waitcnt vmcnt(6)
	v_lshlrev_b32_e32 v104, 16, v87
	v_mul_f32_e32 v79, 0xbfb8aa3b, v104
	v_exp_f32_e32 v79, v79
	v_cvt_pk_bf16_f32 v93, v90, v91
	v_add_co_u32_e32 v90, vcc, s0, v138
	v_cvt_pk_bf16_f32 v95, v96, v97
	s_nop 0
	v_addc_co_u32_e32 v91, vcc, 0, v139, vcc
	global_store_dwordx4 v[90:91], v[92:95], off
	v_lshlrev_b32_e32 v96, 16, v81
	v_and_b32_e32 v97, 0xffff0000, v81
	v_lshlrev_b32_e32 v94, 16, v85
	v_and_b32_e32 v95, 0xffff0000, v85
	v_lshlrev_b32_e32 v98, 16, v84
	v_and_b32_e32 v99, 0xffff0000, v84
	v_lshlrev_b32_e32 v84, 16, v80
	v_and_b32_e32 v85, 0xffff0000, v80
	v_lshlrev_b32_e32 v80, 16, v88
	v_and_b32_e32 v81, 0xffff0000, v88
	v_and_b32_e32 v105, 0xffff0000, v87
	v_add_f32_e32 v79, 1.0, v79
	v_pk_add_f32 v[84:85], v[98:99], v[84:85]
	v_mul_f32_e32 v98, 0xbfb8aa3b, v80
	v_mul_f32_e32 v99, 0xbfb8aa3b, v81
	v_rcp_f32_e32 v106, v79
	v_mul_f32_e32 v79, 0xbfb8aa3b, v105
	v_exp_f32_e32 v98, v98
	v_exp_f32_e32 v99, v99
	v_exp_f32_e32 v79, v79
	v_lshlrev_b32_e32 v92, 16, v89
	v_add_f32_e32 v98, 1.0, v98
	v_add_f32_e32 v99, 1.0, v99
	v_add_f32_e32 v79, 1.0, v79
	v_rcp_f32_e32 v98, v98
	v_rcp_f32_e32 v99, v99
	v_rcp_f32_e32 v107, v79
	v_and_b32_e32 v79, 0xffff0000, v86
	v_and_b32_e32 v93, 0xffff0000, v89
	v_pk_mul_f32 v[80:81], v[98:99], v[80:81]
	v_lshlrev_b32_e32 v98, 16, v83
	v_and_b32_e32 v99, 0xffff0000, v83
	v_pk_mul_f32 v[104:105], v[106:107], v[104:105]
	v_lshlrev_b32_e32 v106, 16, v82
	v_and_b32_e32 v107, 0xffff0000, v82
	v_lshlrev_b32_e32 v82, 16, v78
	v_and_b32_e32 v83, 0xffff0000, v78
	v_pk_add_f32 v[82:83], v[106:107], v[82:83]
	v_pk_add_f32 v[98:99], v[98:99], v[100:101]
	v_lshlrev_b32_e32 v78, 16, v86
	v_pk_mul_f32 v[86:87], v[82:83], v[82:83]
	v_pk_mul_f32 v[100:101], v[98:99], v[98:99]
	v_add_f32_e32 v86, v86, v87
	v_add_f32_e32 v86, v100, v86
	v_pk_mul_f32 v[88:89], v[84:85], v[84:85]
	v_add_f32_e32 v86, v101, v86
	v_pk_add_f32 v[94:95], v[94:95], v[96:97]
	v_add_f32_e32 v86, v88, v86
	v_pk_mul_f32 v[96:97], v[94:95], v[94:95]
	v_add_f32_e32 v86, v89, v86
	v_add_f32_e32 v86, v96, v86
	v_add_f32_e32 v86, v97, v86
	v_mul_f32_e32 v106, 0xbfb8aa3b, v78
	v_mul_f32_e32 v107, 0xbfb8aa3b, v79
	v_add_f32_dpp v86, v86, v86 quad_perm:[1,0,3,2] row_mask:0xf bank_mask:0xf bound_ctrl:1
	v_exp_f32_e32 v106, v106
	v_exp_f32_e32 v107, v107
	v_add_f32_dpp v86, v86, v86 quad_perm:[2,3,0,1] row_mask:0xf bank_mask:0xf bound_ctrl:1
	v_add_f32_e32 v106, 1.0, v106
	s_nop 0
	v_add_f32_dpp v86, v86, v86 row_half_mirror row_mask:0xf bank_mask:0xf bound_ctrl:1
	v_add_f32_e32 v107, 1.0, v107
	v_rcp_f32_e32 v106, v106
	v_add_f32_dpp v86, v86, v86 row_mirror row_mask:0xf bank_mask:0xf bound_ctrl:1
	v_fmamk_f32 v86, v86, 0x3c000000, v202
	v_cmp_gt_f32_e32 vcc, s25, v86
	v_mul_f32_e32 v87, 0x4f800000, v86
	v_rcp_f32_e32 v107, v107
	v_cndmask_b32_e32 v86, v86, v87, vcc
	v_sqrt_f32_e32 v87, v86
	v_pk_mul_f32 v[78:79], v[106:107], v[78:79]
	v_add_u32_e32 v88, -1, v87
	v_fma_f32 v89, -v88, v87, v86
	v_cmp_ge_f32_e64 s[38:39], 0, v89
	v_add_u32_e32 v89, 1, v87
	s_nop 0
	v_cndmask_b32_e64 v88, v87, v88, s[38:39]
	v_fma_f32 v87, -v89, v87, v86
	v_cmp_lt_f32_e64 s[38:39], 0, v87
	s_nop 1
	v_cndmask_b32_e64 v87, v88, v89, s[38:39]
	v_mul_f32_e32 v88, 0x37800000, v87
	v_cndmask_b32_e32 v87, v87, v88, vcc
	v_cmp_class_f32_e32 vcc, v86, v203
	s_nop 1
	v_cndmask_b32_e32 v86, v87, v86, vcc
	v_div_scale_f32 v87, s[4:5], v86, v86, 1.0
	v_rcp_f32_e32 v88, v87
	s_nop 0
	v_fma_f32 v89, -v87, v88, 1.0
	v_fmac_f32_e32 v88, v89, v88
	v_div_scale_f32 v89, vcc, 1.0, v86, 1.0
	v_mul_f32_e32 v96, v89, v88
	v_fma_f32 v97, -v87, v96, v89
	v_fmac_f32_e32 v96, v97, v88
	v_fma_f32 v87, -v87, v96, v89
	v_div_fmas_f32 v87, v87, v88, v96
	v_div_fixup_f32 v86, v87, v86, 1.0
	v_pk_mul_f32 v[84:85], v[84:85], v[86:87] op_sel_hi:[1,0]
	v_pk_mul_f32 v[82:83], v[82:83], v[86:87] op_sel_hi:[1,0]
	v_pk_mul_f32 v[84:85], v[2:3], v[84:85]
	v_pk_mul_f32 v[82:83], v[6:7], v[82:83]
	v_pk_mul_f32 v[80:81], v[80:81], v[84:85]
	v_mul_f32_e32 v84, 0xbfb8aa3b, v92
	v_mul_f32_e32 v85, 0xbfb8aa3b, v93
	v_exp_f32_e32 v84, v84
	v_exp_f32_e32 v85, v85
	v_pk_mul_f32 v[78:79], v[78:79], v[82:83]
	v_pk_mul_f32 v[82:83], v[98:99], v[86:87] op_sel_hi:[1,0]
	v_add_f32_e32 v84, 1.0, v84
	v_add_f32_e32 v85, 1.0, v85
	v_rcp_f32_e32 v84, v84
	v_rcp_f32_e32 v85, v85
	v_pk_mul_f32 v[86:87], v[94:95], v[86:87] op_sel_hi:[1,0]
	s_waitcnt vmcnt(6)
	v_lshlrev_b32_e32 v88, 16, v75
	v_pk_mul_f32 v[86:87], v[4:5], v[86:87]
	v_pk_mul_f32 v[84:85], v[84:85], v[92:93]
	v_pk_mul_f32 v[82:83], v[8:9], v[82:83]
	v_pk_mul_f32 v[84:85], v[84:85], v[86:87]
	v_lshlrev_b32_e32 v86, 16, v67
	v_and_b32_e32 v87, 0xffff0000, v67
	v_mul_f32_e32 v67, 0xbfb8aa3b, v88
	v_exp_f32_e32 v67, v67
	v_pk_mul_f32 v[82:83], v[104:105], v[82:83]
	v_cvt_pk_bf16_f32 v78, v78, v79
	v_cvt_pk_bf16_f32 v79, v82, v83
	v_cvt_pk_bf16_f32 v80, v80, v81
	v_cvt_pk_bf16_f32 v81, v84, v85
	global_store_dwordx4 v[126:127], v[78:81], off offset:1024
	v_lshlrev_b32_e32 v82, 16, v69
	v_and_b32_e32 v83, 0xffff0000, v69
	v_lshlrev_b32_e32 v80, 16, v73
	v_and_b32_e32 v81, 0xffff0000, v73
	v_lshlrev_b32_e32 v84, 16, v72
	v_and_b32_e32 v85, 0xffff0000, v72
	v_lshlrev_b32_e32 v72, 16, v68
	v_and_b32_e32 v73, 0xffff0000, v68
	v_lshlrev_b32_e32 v68, 16, v76
	v_and_b32_e32 v69, 0xffff0000, v76
	v_and_b32_e32 v89, 0xffff0000, v75
	v_add_f32_e32 v67, 1.0, v67
	v_pk_add_f32 v[72:73], v[84:85], v[72:73]
	v_mul_f32_e32 v84, 0xbfb8aa3b, v68
	v_mul_f32_e32 v85, 0xbfb8aa3b, v69
	v_rcp_f32_e32 v92, v67
	v_mul_f32_e32 v67, 0xbfb8aa3b, v89
	v_exp_f32_e32 v84, v84
	v_exp_f32_e32 v85, v85
	v_exp_f32_e32 v67, v67
	v_lshlrev_b32_e32 v78, 16, v77
	v_add_f32_e32 v84, 1.0, v84
	v_add_f32_e32 v85, 1.0, v85
	v_add_f32_e32 v67, 1.0, v67
	v_rcp_f32_e32 v84, v84
	v_rcp_f32_e32 v85, v85
	v_rcp_f32_e32 v93, v67
	v_and_b32_e32 v67, 0xffff0000, v74
	v_and_b32_e32 v79, 0xffff0000, v77
	v_pk_mul_f32 v[68:69], v[84:85], v[68:69]
	v_lshlrev_b32_e32 v84, 16, v71
	v_and_b32_e32 v85, 0xffff0000, v71
	v_pk_mul_f32 v[88:89], v[92:93], v[88:89]
	v_lshlrev_b32_e32 v92, 16, v70
	v_and_b32_e32 v93, 0xffff0000, v70
	v_lshlrev_b32_e32 v70, 16, v66
	v_and_b32_e32 v71, 0xffff0000, v66
	v_pk_add_f32 v[70:71], v[92:93], v[70:71]
	v_pk_add_f32 v[84:85], v[84:85], v[86:87]
	v_lshlrev_b32_e32 v66, 16, v74
	v_pk_mul_f32 v[74:75], v[70:71], v[70:71]
	v_pk_mul_f32 v[86:87], v[84:85], v[84:85]
	v_add_f32_e32 v74, v74, v75
	v_add_f32_e32 v74, v86, v74
	v_pk_mul_f32 v[76:77], v[72:73], v[72:73]
	v_add_f32_e32 v74, v87, v74
	v_pk_add_f32 v[80:81], v[80:81], v[82:83]
	v_add_f32_e32 v74, v76, v74
	v_pk_mul_f32 v[82:83], v[80:81], v[80:81]
	v_add_f32_e32 v74, v77, v74
	v_add_f32_e32 v74, v82, v74
	v_add_f32_e32 v74, v83, v74
	v_mul_f32_e32 v92, 0xbfb8aa3b, v66
	v_mul_f32_e32 v93, 0xbfb8aa3b, v67
	v_add_f32_dpp v74, v74, v74 quad_perm:[1,0,3,2] row_mask:0xf bank_mask:0xf bound_ctrl:1
	v_exp_f32_e32 v92, v92
	v_exp_f32_e32 v93, v93
	v_add_f32_dpp v74, v74, v74 quad_perm:[2,3,0,1] row_mask:0xf bank_mask:0xf bound_ctrl:1
	v_add_f32_e32 v92, 1.0, v92
	s_nop 0
	v_add_f32_dpp v74, v74, v74 row_half_mirror row_mask:0xf bank_mask:0xf bound_ctrl:1
	v_add_f32_e32 v93, 1.0, v93
	v_rcp_f32_e32 v92, v92
	v_add_f32_dpp v74, v74, v74 row_mirror row_mask:0xf bank_mask:0xf bound_ctrl:1
	ds_bpermute_b32 v75, v146, v74
	v_rcp_f32_e32 v93, v93
	s_waitcnt lgkmcnt(0)
	v_add_f32_e32 v74, v74, v75
	v_fmamk_f32 v74, v74, 0x3b800000, v202
	v_cmp_gt_f32_e32 vcc, s25, v74
	v_mul_f32_e32 v75, 0x4f800000, v74
	v_pk_mul_f32 v[66:67], v[92:93], v[66:67]
	v_cndmask_b32_e32 v74, v74, v75, vcc
	v_sqrt_f32_e32 v75, v74
	s_nop 0
	v_add_u32_e32 v76, -1, v75
	v_fma_f32 v77, -v76, v75, v74
	v_cmp_ge_f32_e64 s[38:39], 0, v77
	v_add_u32_e32 v77, 1, v75
	s_nop 0
	v_cndmask_b32_e64 v76, v75, v76, s[38:39]
	v_fma_f32 v75, -v77, v75, v74
	v_cmp_lt_f32_e64 s[38:39], 0, v75
	s_nop 1
	v_cndmask_b32_e64 v75, v76, v77, s[38:39]
	v_mul_f32_e32 v76, 0x37800000, v75
	v_cndmask_b32_e32 v75, v75, v76, vcc
	v_cmp_class_f32_e32 vcc, v74, v203
	s_nop 1
	v_cndmask_b32_e32 v74, v75, v74, vcc
	v_div_scale_f32 v75, s[4:5], v74, v74, 1.0
	v_rcp_f32_e32 v76, v75
	s_nop 0
	v_fma_f32 v77, -v75, v76, 1.0
	v_fmac_f32_e32 v76, v77, v76
	v_div_scale_f32 v77, vcc, 1.0, v74, 1.0
	v_mul_f32_e32 v82, v77, v76
	v_fma_f32 v83, -v75, v82, v77
	v_fmac_f32_e32 v82, v83, v76
	v_fma_f32 v75, -v75, v82, v77
	v_div_fmas_f32 v75, v75, v76, v82
	v_div_fixup_f32 v74, v75, v74, 1.0
	v_pk_mul_f32 v[72:73], v[72:73], v[74:75] op_sel_hi:[1,0]
	v_pk_mul_f32 v[70:71], v[70:71], v[74:75] op_sel_hi:[1,0]
	v_pk_mul_f32 v[72:73], v[10:11], v[72:73]
	v_pk_mul_f32 v[70:71], v[14:15], v[70:71]
	v_pk_mul_f32 v[68:69], v[68:69], v[72:73]
	v_mul_f32_e32 v72, 0xbfb8aa3b, v78
	v_mul_f32_e32 v73, 0xbfb8aa3b, v79
	v_exp_f32_e32 v72, v72
	v_exp_f32_e32 v73, v73
	v_pk_mul_f32 v[66:67], v[66:67], v[70:71]
	v_pk_mul_f32 v[70:71], v[84:85], v[74:75] op_sel_hi:[1,0]
	v_add_f32_e32 v72, 1.0, v72
	v_add_f32_e32 v73, 1.0, v73
	v_rcp_f32_e32 v72, v72
	v_rcp_f32_e32 v73, v73
	v_pk_mul_f32 v[74:75], v[80:81], v[74:75] op_sel_hi:[1,0]
	v_pk_mul_f32 v[70:71], v[16:17], v[70:71]
	v_pk_mul_f32 v[74:75], v[12:13], v[74:75]
	v_pk_mul_f32 v[72:73], v[72:73], v[78:79]
	v_pk_mul_f32 v[70:71], v[88:89], v[70:71]
	v_pk_mul_f32 v[72:73], v[72:73], v[74:75]
	v_cvt_pk_bf16_f32 v66, v66, v67
	v_cvt_pk_bf16_f32 v67, v70, v71
	v_cvt_pk_bf16_f32 v68, v68, v69
	v_cvt_pk_bf16_f32 v69, v72, v73
	global_store_dwordx4 v[126:127], v[66:69], off offset:3072
	v_lshlrev_b32_e32 v70, 16, v57
	v_and_b32_e32 v71, 0xffff0000, v57
	v_lshlrev_b32_e32 v68, 16, v61
	v_and_b32_e32 v69, 0xffff0000, v61
	v_pk_add_f32 v[68:69], v[68:69], v[70:71]
	v_lshlrev_b32_e32 v70, 16, v60
	v_and_b32_e32 v71, 0xffff0000, v60
	v_lshlrev_b32_e32 v60, 16, v56
	v_and_b32_e32 v61, 0xffff0000, v56
	s_waitcnt vmcnt(6)
	v_lshlrev_b32_e32 v56, 16, v64
	v_and_b32_e32 v57, 0xffff0000, v64
	v_lshlrev_b32_e32 v66, 16, v65
	v_and_b32_e32 v67, 0xffff0000, v65
	v_mul_f32_e32 v64, 0xbfb8aa3b, v56
	v_mul_f32_e32 v65, 0xbfb8aa3b, v57
	v_exp_f32_e32 v64, v64
	v_exp_f32_e32 v65, v65
	v_lshlrev_b32_e32 v72, 16, v63
	v_pk_add_f32 v[60:61], v[70:71], v[60:61]
	v_add_f32_e32 v64, 1.0, v64
	v_add_f32_e32 v65, 1.0, v65
	v_lshlrev_b32_e32 v70, 16, v55
	v_and_b32_e32 v71, 0xffff0000, v55
	v_mul_f32_e32 v55, 0xbfb8aa3b, v72
	v_rcp_f32_e32 v64, v64
	v_rcp_f32_e32 v65, v65
	v_exp_f32_e32 v55, v55
	v_and_b32_e32 v73, 0xffff0000, v63
	v_pk_mul_f32 v[56:57], v[64:65], v[56:57]
	v_lshlrev_b32_e32 v64, 16, v59
	v_and_b32_e32 v65, 0xffff0000, v59
	v_add_f32_e32 v55, 1.0, v55
	v_pk_add_f32 v[64:65], v[64:65], v[70:71]
	v_rcp_f32_e32 v70, v55
	v_mul_f32_e32 v55, 0xbfb8aa3b, v73
	v_exp_f32_e32 v55, v55
	v_and_b32_e32 v59, 0xffff0000, v54
	v_add_f32_e32 v55, 1.0, v55
	v_rcp_f32_e32 v71, v55
	v_and_b32_e32 v55, 0xffff0000, v62
	v_mul_f32_e32 v63, 0xbfb8aa3b, v55
	v_exp_f32_e32 v63, v63
	v_pk_mul_f32 v[70:71], v[70:71], v[72:73]
	v_lshlrev_b32_e32 v72, 16, v58
	v_and_b32_e32 v73, 0xffff0000, v58
	v_lshlrev_b32_e32 v58, 16, v54
	v_pk_add_f32 v[58:59], v[72:73], v[58:59]
	v_lshlrev_b32_e32 v54, 16, v62
	v_add_f32_e32 v62, 0, v58
	v_add_f32_e32 v72, v59, v62
	v_mul_f32_e32 v62, 0xbfb8aa3b, v54
	v_exp_f32_e32 v62, v62
	v_add_f32_e32 v63, 1.0, v63
	v_rcp_f32_e32 v63, v63
	v_add_f32_e32 v62, 1.0, v62
	v_rcp_f32_e32 v62, v62
	s_nop 0
	v_pk_mul_f32 v[54:55], v[62:63], v[54:55]
	v_add_f32_e32 v62, v64, v72
	v_add_f32_e32 v62, v65, v62
	v_add_f32_e32 v62, v60, v62
	v_add_f32_e32 v62, v61, v62
	v_add_f32_e32 v62, v68, v62
	v_add_f32_e32 v62, v69, v62
	s_nop 1
	v_add_f32_dpp v62, v62, v62 quad_perm:[1,0,3,2] row_mask:0xf bank_mask:0xf bound_ctrl:1
	s_nop 1
	v_add_f32_dpp v62, v62, v62 quad_perm:[2,3,0,1] row_mask:0xf bank_mask:0xf bound_ctrl:1
	s_nop 1
	v_add_f32_dpp v62, v62, v62 row_half_mirror row_mask:0xf bank_mask:0xf bound_ctrl:1
	s_nop 1
	v_add_f32_dpp v62, v62, v62 row_mirror row_mask:0xf bank_mask:0xf bound_ctrl:1
	ds_bpermute_b32 v63, v146, v62
	s_waitcnt lgkmcnt(0)
	v_add_f32_e32 v62, v62, v63
	v_mul_f32_e32 v62, 0x3b800000, v62
	v_pk_add_f32 v[58:59], v[58:59], v[62:63] op_sel_hi:[1,0] neg_lo:[0,1] neg_hi:[0,1]
	v_pk_add_f32 v[64:65], v[64:65], v[62:63] op_sel_hi:[1,0] neg_lo:[0,1] neg_hi:[0,1]
	v_pk_mul_f32 v[72:73], v[58:59], v[58:59]
	v_pk_mul_f32 v[74:75], v[64:65], v[64:65]
	v_add_f32_e32 v72, v72, v73
	v_pk_add_f32 v[60:61], v[60:61], v[62:63] op_sel_hi:[1,0] neg_lo:[0,1] neg_hi:[0,1]
	v_add_f32_e32 v72, v74, v72
	v_pk_mul_f32 v[76:77], v[60:61], v[60:61]
	v_add_f32_e32 v72, v75, v72
	v_pk_add_f32 v[62:63], v[68:69], v[62:63] op_sel_hi:[1,0] neg_lo:[0,1] neg_hi:[0,1]
	v_add_f32_e32 v72, v76, v72
	v_pk_mul_f32 v[68:69], v[62:63], v[62:63]
	v_add_f32_e32 v72, v77, v72
	v_add_f32_e32 v68, v68, v72
	v_add_f32_e32 v68, v69, v68
	s_nop 1
	v_add_f32_dpp v68, v68, v68 quad_perm:[1,0,3,2] row_mask:0xf bank_mask:0xf bound_ctrl:1
	s_nop 1
	v_add_f32_dpp v68, v68, v68 quad_perm:[2,3,0,1] row_mask:0xf bank_mask:0xf bound_ctrl:1
	s_nop 1
	v_add_f32_dpp v68, v68, v68 row_half_mirror row_mask:0xf bank_mask:0xf bound_ctrl:1
	s_nop 1
	v_add_f32_dpp v68, v68, v68 row_mirror row_mask:0xf bank_mask:0xf bound_ctrl:1
	ds_bpermute_b32 v69, v146, v68
	s_waitcnt lgkmcnt(0)
	v_add_f32_e32 v68, v68, v69
	v_fmamk_f32 v68, v68, 0x3b800000, v202
	v_cmp_gt_f32_e32 vcc, s25, v68
	v_mul_f32_e32 v69, 0x4f800000, v68
	s_nop 0
	v_cndmask_b32_e32 v68, v68, v69, vcc
	v_sqrt_f32_e32 v69, v68
	s_nop 0
	v_add_u32_e32 v72, -1, v69
	v_fma_f32 v73, -v72, v69, v68
	v_cmp_ge_f32_e64 s[38:39], 0, v73
	v_add_u32_e32 v73, 1, v69
	s_nop 0
	v_cndmask_b32_e64 v72, v69, v72, s[38:39]
	v_fma_f32 v69, -v73, v69, v68
	v_cmp_lt_f32_e64 s[38:39], 0, v69
	s_nop 1
	v_cndmask_b32_e64 v69, v72, v73, s[38:39]
	v_mul_f32_e32 v72, 0x37800000, v69
	v_cndmask_b32_e32 v69, v69, v72, vcc
	v_cmp_class_f32_e32 vcc, v68, v203
	s_nop 1
	v_cndmask_b32_e32 v68, v69, v68, vcc
	v_div_scale_f32 v69, s[4:5], v68, v68, 1.0
	v_rcp_f32_e32 v72, v69
	s_nop 0
	v_fma_f32 v73, -v69, v72, 1.0
	v_fmac_f32_e32 v72, v73, v72
	v_div_scale_f32 v73, vcc, 1.0, v68, 1.0
	v_mul_f32_e32 v74, v73, v72
	v_fma_f32 v75, -v69, v74, v73
	v_fmac_f32_e32 v74, v75, v72
	v_fma_f32 v69, -v69, v74, v73
	v_div_fmas_f32 v69, v69, v72, v74
	v_div_fixup_f32 v68, v69, v68, 1.0
	v_pk_mul_f32 v[60:61], v[60:61], v[68:69] op_sel_hi:[1,0]
	v_pk_mul_f32 v[58:59], v[58:59], v[68:69] op_sel_hi:[1,0]
	v_pk_mul_f32 v[60:61], v[18:19], v[60:61]
	v_pk_mul_f32 v[58:59], v[22:23], v[58:59]
	v_pk_mul_f32 v[56:57], v[56:57], v[60:61]
	v_mul_f32_e32 v60, 0xbfb8aa3b, v66
	v_mul_f32_e32 v61, 0xbfb8aa3b, v67
	v_exp_f32_e32 v60, v60
	v_exp_f32_e32 v61, v61
	v_pk_mul_f32 v[54:55], v[54:55], v[58:59]
	v_pk_mul_f32 v[58:59], v[64:65], v[68:69] op_sel_hi:[1,0]
	v_add_f32_e32 v60, 1.0, v60
	v_add_f32_e32 v61, 1.0, v61
	v_rcp_f32_e32 v60, v60
	v_rcp_f32_e32 v61, v61
	v_pk_mul_f32 v[62:63], v[62:63], v[68:69] op_sel_hi:[1,0]
	v_pk_mul_f32 v[58:59], v[24:25], v[58:59]
	v_pk_mul_f32 v[62:63], v[20:21], v[62:63]
	v_pk_mul_f32 v[60:61], v[60:61], v[66:67]
	v_pk_mul_f32 v[58:59], v[70:71], v[58:59]
	v_pk_mul_f32 v[60:61], v[60:61], v[62:63]
	v_cvt_pk_bf16_f32 v54, v54, v55
	v_cvt_pk_bf16_f32 v55, v58, v59
	v_cvt_pk_bf16_f32 v56, v56, v57
	v_cvt_pk_bf16_f32 v57, v60, v61
	global_store_dwordx4 v[102:103], v[54:57], off offset:3072
	v_lshlrev_b32_e32 v58, 16, v50
	v_and_b32_e32 v59, 0xffff0000, v50
	v_lshlrev_b32_e32 v54, 16, v46
	v_and_b32_e32 v55, 0xffff0000, v46
	v_lshlrev_b32_e32 v56, 16, v42
	v_and_b32_e32 v57, 0xffff0000, v42
	v_pk_add_f32 v[54:55], v[54:55], v[56:57]
	s_nop 0
	v_pk_fma_f32 v[54:55], v[38:39], v[58:59], v[54:55]
	s_nop 0
	v_mul_f32_e32 v42, 0x3d372713, v54
	v_mul_f32_e32 v42, v54, v42
	v_fma_f32 v42, v54, v42, v54
	v_mul_f32_e32 v42, 0x3f4c422a, v42
	v_add_f32_e32 v42, v42, v42
	v_mul_f32_e32 v42, 0x3fb8aa3b, v42
	v_exp_f32_e32 v56, v42
	v_mul_f32_e32 v42, 0x3d372713, v55
	v_mul_f32_e32 v42, v55, v42
	v_fma_f32 v42, v55, v42, v55
	v_mul_f32_e32 v42, 0x3f4c422a, v42
	v_add_f32_e32 v42, v42, v42
	v_mul_f32_e32 v42, 0x3fb8aa3b, v42
	v_exp_f32_e32 v57, v42
	v_pk_mul_f32 v[54:55], v[54:55], 0.5 op_sel_hi:[1,0]
	v_pk_add_f32 v[56:57], v[56:57], 1.0 op_sel_hi:[1,0]
	s_nop 0
	v_div_scale_f32 v42, s[4:5], v57, v57, 2.0
	v_rcp_f32_e32 v46, v42
	s_nop 0
	v_fma_f32 v50, -v42, v46, 1.0
	v_fmac_f32_e32 v46, v50, v46
	v_div_scale_f32 v50, vcc, 2.0, v57, 2.0
	v_mul_f32_e32 v58, v50, v46
	v_fma_f32 v59, -v42, v58, v50
	v_fmac_f32_e32 v58, v59, v46
	v_fma_f32 v42, -v42, v58, v50
	v_div_fmas_f32 v42, v42, v46, v58
	v_div_fixup_f32 v57, v42, v57, 2.0
	v_div_scale_f32 v42, s[4:5], v56, v56, 2.0
	v_rcp_f32_e32 v46, v42
	s_nop 0
	v_fma_f32 v50, -v42, v46, 1.0
	v_fmac_f32_e32 v46, v50, v46
	v_div_scale_f32 v50, vcc, 2.0, v56, 2.0
	v_mul_f32_e32 v58, v50, v46
	v_fma_f32 v59, -v42, v58, v50
	v_fmac_f32_e32 v58, v59, v46
	v_fma_f32 v42, -v42, v58, v50
	v_div_fmas_f32 v42, v42, v46, v58
	v_div_fixup_f32 v56, v42, v56, 2.0
	v_lshlrev_b32_e32 v46, 16, v47
	v_and_b32_e32 v47, 0xffff0000, v47
	v_lshlrev_b32_e32 v42, 16, v43
	v_and_b32_e32 v43, 0xffff0000, v43
	v_lshlrev_b32_e32 v50, 16, v51
	v_and_b32_e32 v51, 0xffff0000, v51
	v_pk_add_f32 v[42:43], v[46:47], v[42:43]
	v_pk_add_f32 v[56:57], v[56:57], 1.0 op_sel_hi:[1,0] neg_lo:[1,0] neg_hi:[1,0]
	v_pk_fma_f32 v[42:43], v[40:41], v[50:51], v[42:43]
	v_pk_add_f32 v[56:57], v[56:57], 1.0 op_sel_hi:[1,0]
	v_mul_f32_e32 v46, 0x3d372713, v42
	v_mul_f32_e32 v47, 0x3d372713, v43
	v_mul_f32_e32 v46, v42, v46
	v_mul_f32_e32 v47, v43, v47
	v_fma_f32 v46, v42, v46, v42
	v_fma_f32 v47, v43, v47, v43
	v_mul_f32_e32 v46, 0x3f4c422a, v46
	v_mul_f32_e32 v47, 0x3f4c422a, v47
	v_add_f32_e32 v46, v46, v46
	v_add_f32_e32 v47, v47, v47
	v_mul_f32_e32 v46, 0x3fb8aa3b, v46
	v_mul_f32_e32 v47, 0x3fb8aa3b, v47
	v_exp_f32_e32 v46, v46
	v_exp_f32_e32 v47, v47
	v_pk_mul_f32 v[54:55], v[54:55], v[56:57]
	v_pk_mul_f32 v[42:43], v[42:43], 0.5 op_sel_hi:[1,0]
	v_pk_add_f32 v[46:47], v[46:47], 1.0 op_sel_hi:[1,0]
	s_nop 0
	v_div_scale_f32 v50, s[4:5], v47, v47, 2.0
	v_rcp_f32_e32 v51, v50
	s_nop 0
	v_fma_f32 v56, -v50, v51, 1.0
	v_fmac_f32_e32 v51, v56, v51
	v_div_scale_f32 v56, vcc, 2.0, v47, 2.0
	v_mul_f32_e32 v57, v56, v51
	v_fma_f32 v58, -v50, v57, v56
	v_fmac_f32_e32 v57, v58, v51
	v_fma_f32 v50, -v50, v57, v56
	v_div_fmas_f32 v50, v50, v51, v57
	v_div_fixup_f32 v47, v50, v47, 2.0
	v_div_scale_f32 v50, s[4:5], v46, v46, 2.0
	v_rcp_f32_e32 v51, v50
	s_nop 0
	v_fma_f32 v56, -v50, v51, 1.0
	v_fmac_f32_e32 v51, v56, v51
	v_div_scale_f32 v56, vcc, 2.0, v46, 2.0
	v_mul_f32_e32 v57, v56, v51
	v_fma_f32 v58, -v50, v57, v56
	v_fmac_f32_e32 v57, v58, v51
	v_fma_f32 v50, -v50, v57, v56
	v_div_fmas_f32 v50, v50, v51, v57
	v_div_fixup_f32 v46, v50, v46, 2.0
	v_pk_add_f32 v[46:47], v[46:47], 1.0 op_sel_hi:[1,0] neg_lo:[1,0] neg_hi:[1,0]
	v_lshlrev_b32_e32 v50, 16, v44
	v_pk_add_f32 v[46:47], v[46:47], 1.0 op_sel_hi:[1,0]
	v_and_b32_e32 v51, 0xffff0000, v44
	v_pk_mul_f32 v[42:43], v[42:43], v[46:47]
	v_lshlrev_b32_e32 v46, 16, v48
	v_and_b32_e32 v47, 0xffff0000, v48
	v_lshlrev_b32_e32 v56, 16, v52
	v_and_b32_e32 v57, 0xffff0000, v52
	v_pk_add_f32 v[46:47], v[46:47], v[50:51]
	s_nop 0
	v_pk_fma_f32 v[46:47], v[34:35], v[56:57], v[46:47]
	s_nop 0
	v_mul_f32_e32 v44, 0x3d372713, v46
	v_mul_f32_e32 v44, v46, v44
	v_fma_f32 v44, v46, v44, v46
	v_mul_f32_e32 v44, 0x3f4c422a, v44
	v_add_f32_e32 v44, v44, v44
	v_mul_f32_e32 v44, 0x3fb8aa3b, v44
	v_exp_f32_e32 v50, v44
	v_mul_f32_e32 v44, 0x3d372713, v47
	v_mul_f32_e32 v44, v47, v44
	v_fma_f32 v44, v47, v44, v47
	v_mul_f32_e32 v44, 0x3f4c422a, v44
	v_add_f32_e32 v44, v44, v44
	v_mul_f32_e32 v44, 0x3fb8aa3b, v44
	v_exp_f32_e32 v51, v44
	v_pk_mul_f32 v[46:47], v[46:47], 0.5 op_sel_hi:[1,0]
	v_pk_add_f32 v[50:51], v[50:51], 1.0 op_sel_hi:[1,0]
	s_nop 0
	v_div_scale_f32 v44, s[4:5], v51, v51, 2.0
	v_rcp_f32_e32 v48, v44
	s_nop 0
	v_fma_f32 v52, -v44, v48, 1.0
	v_fmac_f32_e32 v48, v52, v48
	v_div_scale_f32 v52, vcc, 2.0, v51, 2.0
	v_mul_f32_e32 v56, v52, v48
	v_fma_f32 v57, -v44, v56, v52
	v_fmac_f32_e32 v56, v57, v48
	v_fma_f32 v44, -v44, v56, v52
	v_div_fmas_f32 v44, v44, v48, v56
	v_div_fixup_f32 v51, v44, v51, 2.0
	v_div_scale_f32 v44, s[4:5], v50, v50, 2.0
	v_rcp_f32_e32 v48, v44
	s_nop 0
	v_fma_f32 v52, -v44, v48, 1.0
	v_fmac_f32_e32 v48, v52, v48
	v_div_scale_f32 v52, vcc, 2.0, v50, 2.0
	v_mul_f32_e32 v56, v52, v48
	v_fma_f32 v57, -v44, v56, v52
	v_fmac_f32_e32 v56, v57, v48
	v_fma_f32 v44, -v44, v56, v52
	v_div_fmas_f32 v44, v44, v48, v56
	v_div_fixup_f32 v50, v44, v50, 2.0
	v_pk_add_f32 v[50:51], v[50:51], 1.0 op_sel_hi:[1,0] neg_lo:[1,0] neg_hi:[1,0]
	v_lshlrev_b32_e32 v48, 16, v49
	v_pk_add_f32 v[50:51], v[50:51], 1.0 op_sel_hi:[1,0]
	v_and_b32_e32 v49, 0xffff0000, v49
	v_lshlrev_b32_e32 v44, 16, v45
	v_and_b32_e32 v45, 0xffff0000, v45
	v_pk_mul_f32 v[46:47], v[46:47], v[50:51]
	v_lshlrev_b32_e32 v50, 16, v53
	v_and_b32_e32 v51, 0xffff0000, v53
	v_pk_add_f32 v[44:45], v[48:49], v[44:45]
	v_cvt_pk_bf16_f32 v46, v46, v47
	v_pk_fma_f32 v[44:45], v[36:37], v[50:51], v[44:45]
	s_nop 0
	v_mul_f32_e32 v48, 0x3d372713, v44
	v_mul_f32_e32 v49, 0x3d372713, v45
	v_mul_f32_e32 v48, v44, v48
	v_mul_f32_e32 v49, v45, v49
	v_fma_f32 v48, v44, v48, v44
	v_fma_f32 v49, v45, v49, v45
	v_mul_f32_e32 v48, 0x3f4c422a, v48
	v_mul_f32_e32 v49, 0x3f4c422a, v49
	v_add_f32_e32 v48, v48, v48
	v_add_f32_e32 v49, v49, v49
	v_mul_f32_e32 v48, 0x3fb8aa3b, v48
	v_mul_f32_e32 v49, 0x3fb8aa3b, v49
	v_exp_f32_e32 v48, v48
	v_exp_f32_e32 v49, v49
	v_pk_mul_f32 v[44:45], v[44:45], 0.5 op_sel_hi:[1,0]
	v_pk_add_f32 v[48:49], v[48:49], 1.0 op_sel_hi:[1,0]
	s_nop 0
	v_div_scale_f32 v50, s[4:5], v49, v49, 2.0
	v_rcp_f32_e32 v51, v50
	s_nop 0
	v_fma_f32 v52, -v50, v51, 1.0
	v_fmac_f32_e32 v51, v52, v51
	v_div_scale_f32 v52, vcc, 2.0, v49, 2.0
	v_mul_f32_e32 v53, v52, v51
	v_fma_f32 v56, -v50, v53, v52
	v_fmac_f32_e32 v53, v56, v51
	v_fma_f32 v50, -v50, v53, v52
	v_div_fmas_f32 v50, v50, v51, v53
	v_div_fixup_f32 v49, v50, v49, 2.0
	v_div_scale_f32 v50, s[4:5], v48, v48, 2.0
	v_rcp_f32_e32 v51, v50
	s_nop 0
	v_fma_f32 v52, -v50, v51, 1.0
	v_fmac_f32_e32 v51, v52, v51
	v_div_scale_f32 v52, vcc, 2.0, v48, 2.0
	v_mul_f32_e32 v53, v52, v51
	v_fma_f32 v56, -v50, v53, v52
	v_fmac_f32_e32 v53, v56, v51
	v_fma_f32 v50, -v50, v53, v52
	v_div_fmas_f32 v50, v50, v51, v53
	v_div_fixup_f32 v48, v50, v48, 2.0
	v_pk_add_f32 v[48:49], v[48:49], 1.0 op_sel_hi:[1,0] neg_lo:[1,0] neg_hi:[1,0]
	s_nop 0
	v_pk_add_f32 v[48:49], v[48:49], 1.0 op_sel_hi:[1,0]
	s_nop 0
	v_pk_mul_f32 v[48:49], v[44:45], v[48:49]
	v_cvt_pk_bf16_f32 v44, v54, v55
	v_cvt_pk_bf16_f32 v45, v42, v43
	v_cvt_pk_bf16_f32 v47, v48, v49
	global_store_dwordx4 v[90:91], v[44:47], off offset:1024
	s_branch .LBB0_621
